# non-temporal (nt) loads also for the post phase's once-read rows and the weight-conversion source tiles
# speedup vs baseline: 1.0141x; 1.0141x over previous
.Lwc0_tj_1:
	s_load_dwordx2 s[2:3], s[0:1], s41
	s_add_u32 s52, s4, s36
	s_addc_u32 s53, s5, 0
	v_mad_u32_u24 v223, v225, s99, v226
	v_writelane_b32 v229, s52, 8
	v_writelane_b32 v229, s53, 9
	v_writelane_b32 v229, s32, 10
	v_writelane_b32 v229, s44, 11
	s_add_u32 s100, s100, s67
	s_waitcnt lgkmcnt(0)
	s_add_u32 s38, s2, s38
	s_addc_u32 s39, s3, 0
	global_load_dwordx4 v[138:141], v223, s[38:39] nt
	s_add_u32 s38, s38, s37
	s_addc_u32 s39, s39, 0
	global_load_dwordx4 v[142:145], v223, s[38:39] nt
	s_add_u32 s38, s38, s37
	s_addc_u32 s39, s39, 0
	global_load_dwordx4 v[146:149], v223, s[38:39] nt
	s_add_u32 s38, s38, s37
	s_addc_u32 s39, s39, 0
	global_load_dwordx4 v[150:153], v223, s[38:39] nt
	s_cmp_ge_u32 s100, s66
	s_cbranch_scc1 .Lwc0_p1
	s_cmpk_ge_u32 s100, 0x900
	s_cbranch_scc1 .Lwc0_t3_2
	s_cmpk_ge_u32 s100, 0x380
	s_cbranch_scc1 .Lwc0_t2_2
	s_cmpk_ge_u32 s100, 0x280
	s_cbranch_scc1 .Lwc0_t1_2
	s_movk_i32 s41, 0x78
	s_sub_u32 s99, s100, 0
	s_mul_i32 s44, s99, 0x66667
	s_lshr_b32 s44, s44, 24
	s_mul_i32 s36, s44, 40
	s_sub_u32 s99, s99, s36
	s_mul_i32 s38, s44, 0xa0000
	s_lshl_b32 s36, s99, 8
	s_add_u32 s38, s38, s36
	s_add_u32 s38, s38, 0x0
	s_lshl_b32 s36, s99, 6
	s_mov_b32 s32, 0x10000
	s_mul_i32 s36, s36, 0x800
	s_lshl_b32 s44, s44, 7
	s_add_u32 s36, s36, s44
	s_add_u32 s36, s36, 0x0
	s_mov_b32 s37, 0x28000
	s_movk_i32 s44, 0x800
	s_mov_b32 s99, 0x2800
	s_branch .Lwc0_tj_2

.Lwc0_tj_2:
	s_load_dwordx2 s[2:3], s[0:1], s41
	s_add_u32 s52, s4, s36
	s_addc_u32 s53, s5, 0
	v_mad_u32_u24 v223, v225, s99, v226
	v_writelane_b32 v229, s52, 12
	v_writelane_b32 v229, s53, 13
	v_writelane_b32 v229, s32, 14
	v_writelane_b32 v229, s44, 15
	s_add_u32 s100, s100, s67
	s_waitcnt lgkmcnt(0)
	s_add_u32 s38, s2, s38
	s_addc_u32 s39, s3, 0
	global_load_dwordx4 v[154:157], v223, s[38:39] nt
	s_add_u32 s38, s38, s37
	s_addc_u32 s39, s39, 0
	global_load_dwordx4 v[158:161], v223, s[38:39] nt
	s_add_u32 s38, s38, s37
	s_addc_u32 s39, s39, 0
	global_load_dwordx4 v[162:165], v223, s[38:39] nt
	s_add_u32 s38, s38, s37
	s_addc_u32 s39, s39, 0
	global_load_dwordx4 v[166:169], v223, s[38:39] nt
	s_cmp_ge_u32 s100, s66
	s_cbranch_scc1 .Lwc0_p2
	s_cmpk_ge_u32 s100, 0x900
	s_cbranch_scc1 .Lwc0_t3_3
	s_cmpk_ge_u32 s100, 0x380
	s_cbranch_scc1 .Lwc0_t2_3
	s_cmpk_ge_u32 s100, 0x280
	s_cbranch_scc1 .Lwc0_t1_3
	s_movk_i32 s41, 0x78
	s_sub_u32 s99, s100, 0
	s_mul_i32 s44, s99, 0x66667
	s_lshr_b32 s44, s44, 24
	s_mul_i32 s36, s44, 40
	s_sub_u32 s99, s99, s36
	s_mul_i32 s38, s44, 0xa0000
	s_lshl_b32 s36, s99, 8
	s_add_u32 s38, s38, s36
	s_add_u32 s38, s38, 0x0
	s_lshl_b32 s36, s99, 6
	s_mov_b32 s32, 0x10000
	s_mul_i32 s36, s36, 0x800
	s_lshl_b32 s44, s44, 7
	s_add_u32 s36, s36, s44
	s_add_u32 s36, s36, 0x0
	s_mov_b32 s37, 0x28000
	s_movk_i32 s44, 0x800
	s_mov_b32 s99, 0x2800
	s_branch .Lwc0_tj_3

.Lwc0_tj_3:
	s_load_dwordx2 s[2:3], s[0:1], s41
	s_add_u32 s52, s4, s36
	s_addc_u32 s53, s5, 0
	v_mad_u32_u24 v223, v225, s99, v226
	v_writelane_b32 v229, s52, 16
	v_writelane_b32 v229, s53, 17
	v_writelane_b32 v229, s32, 18
	v_writelane_b32 v229, s44, 19
	s_add_u32 s100, s100, s67
	s_waitcnt lgkmcnt(0)
	s_add_u32 s38, s2, s38
	s_addc_u32 s39, s3, 0
	global_load_dwordx4 v[170:173], v223, s[38:39] nt
	s_add_u32 s38, s38, s37
	s_addc_u32 s39, s39, 0
	global_load_dwordx4 v[174:177], v223, s[38:39] nt
	s_add_u32 s38, s38, s37
	s_addc_u32 s39, s39, 0
	global_load_dwordx4 v[178:181], v223, s[38:39] nt
	s_add_u32 s38, s38, s37
	s_addc_u32 s39, s39, 0
	global_load_dwordx4 v[182:185], v223, s[38:39] nt

.Lwc0_tj_4:
	s_load_dwordx2 s[2:3], s[0:1], s41
	s_add_u32 s52, s4, s36
	s_addc_u32 s53, s5, 0
	v_mad_u32_u24 v223, v225, s99, v226
	v_writelane_b32 v229, s52, 8
	v_writelane_b32 v229, s53, 9
	v_writelane_b32 v229, s32, 10
	v_writelane_b32 v229, s44, 11
	s_add_u32 s100, s100, s67
	s_waitcnt lgkmcnt(0)
	s_add_u32 s38, s2, s38
	s_addc_u32 s39, s3, 0
	global_load_dwordx4 v[138:141], v223, s[38:39] nt
	s_add_u32 s38, s38, s37
	s_addc_u32 s39, s39, 0
	global_load_dwordx4 v[142:145], v223, s[38:39] nt
	s_add_u32 s38, s38, s37
	s_addc_u32 s39, s39, 0
	global_load_dwordx4 v[146:149], v223, s[38:39] nt
	s_add_u32 s38, s38, s37
	s_addc_u32 s39, s39, 0
	global_load_dwordx4 v[150:153], v223, s[38:39] nt
	s_waitcnt vmcnt(8)
	v_readlane_b32 s52, v229, 12
	v_readlane_b32 s53, v229, 13
	v_readlane_b32 s32, v229, 14
	v_readlane_b32 s35, v229, 15
	ds_write_b32 v218, v154 offset:0
	ds_write_b32 v218, v155 offset:4
	ds_write_b32 v218, v156 offset:8
	ds_write_b32 v218, v157 offset:12
	ds_write_b32 v218, v158 offset:4160
	ds_write_b32 v218, v159 offset:4164
	ds_write_b32 v218, v160 offset:4168
	ds_write_b32 v218, v161 offset:4172
	ds_write_b32 v218, v162 offset:8320
	ds_write_b32 v218, v163 offset:8324
	ds_write_b32 v218, v164 offset:8328
	ds_write_b32 v218, v165 offset:8332
	ds_write_b32 v218, v166 offset:12480
	ds_write_b32 v218, v167 offset:12484
	ds_write_b32 v218, v168 offset:12488
	ds_write_b32 v218, v169 offset:12492
	v_mad_u32_u24 v224, v227, s35, v228
	s_waitcnt lgkmcnt(0)
	s_barrier
	ds_read2_b32 v[154:155], v219 offset1:65
	ds_read2_b32 v[156:157], v219 offset0:130 offset1:195
	ds_read2_b32 v[158:159], v220 offset0:4 offset1:69
	ds_read2_b32 v[160:161], v220 offset0:134 offset1:199
	ds_read2_b32 v[162:163], v221 offset1:65
	ds_read2_b32 v[164:165], v221 offset0:130 offset1:195
	ds_read2_b32 v[166:167], v222 offset0:4 offset1:69
	ds_read2_b32 v[168:169], v222 offset0:134 offset1:199
	s_add_u32 s96, s52, s32
	s_addc_u32 s97, s53, 0
	s_waitcnt lgkmcnt(0)
	s_barrier
	v_cvt_pk_bf16_f32 v154, v154, v155
	v_cvt_pk_bf16_f32 v155, v156, v157
	v_cvt_pk_bf16_f32 v156, v158, v159
	v_cvt_pk_bf16_f32 v157, v160, v161
	v_cvt_pk_bf16_f32 v162, v162, v163
	v_cvt_pk_bf16_f32 v163, v164, v165
	v_cvt_pk_bf16_f32 v164, v166, v167
	v_cvt_pk_bf16_f32 v165, v168, v169
	global_store_dwordx4 v224, v[154:157], s[52:53]
	global_store_dwordx4 v224, v[162:165], s[96:97]
	s_cmp_ge_u32 s100, s66
	s_cbranch_scc1 .Lwc0_tail1
	s_cmpk_ge_u32 s100, 0x900
	s_cbranch_scc1 .Lwc0_t3_5
	s_cmpk_ge_u32 s100, 0x380
	s_cbranch_scc1 .Lwc0_t2_5
	s_cmpk_ge_u32 s100, 0x280
	s_cbranch_scc1 .Lwc0_t1_5
	s_movk_i32 s41, 0x78
	s_sub_u32 s99, s100, 0
	s_mul_i32 s44, s99, 0x66667
	s_lshr_b32 s44, s44, 24
	s_mul_i32 s36, s44, 40
	s_sub_u32 s99, s99, s36
	s_mul_i32 s38, s44, 0xa0000
	s_lshl_b32 s36, s99, 8
	s_add_u32 s38, s38, s36
	s_add_u32 s38, s38, 0x0
	s_lshl_b32 s36, s99, 6
	s_mov_b32 s32, 0x10000
	s_mul_i32 s36, s36, 0x800
	s_lshl_b32 s44, s44, 7
	s_add_u32 s36, s36, s44
	s_add_u32 s36, s36, 0x0
	s_mov_b32 s37, 0x28000
	s_movk_i32 s44, 0x800
	s_mov_b32 s99, 0x2800
	s_branch .Lwc0_tj_5

.Lwc0_tj_5:
	s_load_dwordx2 s[2:3], s[0:1], s41
	s_add_u32 s52, s4, s36
	s_addc_u32 s53, s5, 0
	v_mad_u32_u24 v223, v225, s99, v226
	v_writelane_b32 v229, s52, 12
	v_writelane_b32 v229, s53, 13
	v_writelane_b32 v229, s32, 14
	v_writelane_b32 v229, s44, 15
	s_add_u32 s100, s100, s67
	s_waitcnt lgkmcnt(0)
	s_add_u32 s38, s2, s38
	s_addc_u32 s39, s3, 0
	global_load_dwordx4 v[154:157], v223, s[38:39] nt
	s_add_u32 s38, s38, s37
	s_addc_u32 s39, s39, 0
	global_load_dwordx4 v[158:161], v223, s[38:39] nt
	s_add_u32 s38, s38, s37
	s_addc_u32 s39, s39, 0
	global_load_dwordx4 v[162:165], v223, s[38:39] nt
	s_add_u32 s38, s38, s37
	s_addc_u32 s39, s39, 0
	global_load_dwordx4 v[166:169], v223, s[38:39] nt
	s_waitcnt vmcnt(8)
	v_readlane_b32 s52, v229, 16
	v_readlane_b32 s53, v229, 17
	v_readlane_b32 s32, v229, 18
	v_readlane_b32 s35, v229, 19
	ds_write_b32 v218, v170 offset:0
	ds_write_b32 v218, v171 offset:4
	ds_write_b32 v218, v172 offset:8
	ds_write_b32 v218, v173 offset:12
	ds_write_b32 v218, v174 offset:4160
	ds_write_b32 v218, v175 offset:4164
	ds_write_b32 v218, v176 offset:4168
	ds_write_b32 v218, v177 offset:4172
	ds_write_b32 v218, v178 offset:8320
	ds_write_b32 v218, v179 offset:8324
	ds_write_b32 v218, v180 offset:8328
	ds_write_b32 v218, v181 offset:8332
	ds_write_b32 v218, v182 offset:12480
	ds_write_b32 v218, v183 offset:12484
	ds_write_b32 v218, v184 offset:12488
	ds_write_b32 v218, v185 offset:12492
	v_mad_u32_u24 v224, v227, s35, v228
	s_waitcnt lgkmcnt(0)
	s_barrier
	ds_read2_b32 v[170:171], v219 offset1:65
	ds_read2_b32 v[172:173], v219 offset0:130 offset1:195
	ds_read2_b32 v[174:175], v220 offset0:4 offset1:69
	ds_read2_b32 v[176:177], v220 offset0:134 offset1:199
	ds_read2_b32 v[178:179], v221 offset1:65
	ds_read2_b32 v[180:181], v221 offset0:130 offset1:195
	ds_read2_b32 v[182:183], v222 offset0:4 offset1:69
	ds_read2_b32 v[184:185], v222 offset0:134 offset1:199
	s_add_u32 s96, s52, s32
	s_addc_u32 s97, s53, 0
	s_waitcnt lgkmcnt(0)
	s_barrier
	v_cvt_pk_bf16_f32 v170, v170, v171
	v_cvt_pk_bf16_f32 v171, v172, v173
	v_cvt_pk_bf16_f32 v172, v174, v175
	v_cvt_pk_bf16_f32 v173, v176, v177
	v_cvt_pk_bf16_f32 v178, v178, v179
	v_cvt_pk_bf16_f32 v179, v180, v181
	v_cvt_pk_bf16_f32 v180, v182, v183
	v_cvt_pk_bf16_f32 v181, v184, v185
	global_store_dwordx4 v224, v[170:173], s[52:53]
	global_store_dwordx4 v224, v[178:181], s[96:97]
	s_cmp_ge_u32 s100, s66
	s_cbranch_scc1 .Lwc0_tail2
	s_cmpk_ge_u32 s100, 0x900
	s_cbranch_scc1 .Lwc0_t3_6
	s_cmpk_ge_u32 s100, 0x380
	s_cbranch_scc1 .Lwc0_t2_6
	s_cmpk_ge_u32 s100, 0x280
	s_cbranch_scc1 .Lwc0_t1_6
	s_movk_i32 s41, 0x78
	s_sub_u32 s99, s100, 0
	s_mul_i32 s44, s99, 0x66667
	s_lshr_b32 s44, s44, 24
	s_mul_i32 s36, s44, 40
	s_sub_u32 s99, s99, s36
	s_mul_i32 s38, s44, 0xa0000
	s_lshl_b32 s36, s99, 8
	s_add_u32 s38, s38, s36
	s_add_u32 s38, s38, 0x0
	s_lshl_b32 s36, s99, 6
	s_mov_b32 s32, 0x10000
	s_mul_i32 s36, s36, 0x800
	s_lshl_b32 s44, s44, 7
	s_add_u32 s36, s36, s44
	s_add_u32 s36, s36, 0x0
	s_mov_b32 s37, 0x28000
	s_movk_i32 s44, 0x800
	s_mov_b32 s99, 0x2800
	s_branch .Lwc0_tj_6

.Lwc0_tj_6:
	s_load_dwordx2 s[2:3], s[0:1], s41
	s_add_u32 s52, s4, s36
	s_addc_u32 s53, s5, 0
	v_mad_u32_u24 v223, v225, s99, v226
	v_writelane_b32 v229, s52, 16
	v_writelane_b32 v229, s53, 17
	v_writelane_b32 v229, s32, 18
	v_writelane_b32 v229, s44, 19
	s_add_u32 s100, s100, s67
	s_waitcnt lgkmcnt(0)
	s_add_u32 s38, s2, s38
	s_addc_u32 s39, s3, 0
	global_load_dwordx4 v[170:173], v223, s[38:39] nt
	s_add_u32 s38, s38, s37
	s_addc_u32 s39, s39, 0
	global_load_dwordx4 v[174:177], v223, s[38:39] nt
	s_add_u32 s38, s38, s37
	s_addc_u32 s39, s39, 0
	global_load_dwordx4 v[178:181], v223, s[38:39] nt
	s_add_u32 s38, s38, s37
	s_addc_u32 s39, s39, 0
	global_load_dwordx4 v[182:185], v223, s[38:39] nt
	s_branch .Lwc0_loop

.Lwcm0_tj_1:
	s_load_dwordx2 s[8:9], s[0:1], s14
	s_add_u32 s20, s12, s36
	s_addc_u32 s21, s13, 0
	v_mad_u32_u24 v231, v233, s99, v234
	v_writelane_b32 v237, s20, 8
	v_writelane_b32 v237, s21, 9
	v_writelane_b32 v237, s32, 10
	v_writelane_b32 v237, s44, 11
	s_add_u32 s100, s100, s23
	s_waitcnt lgkmcnt(0)
	s_add_u32 s38, s8, s38
	s_addc_u32 s39, s9, 0
	global_load_dwordx4 v[146:149], v231, s[38:39] nt
	s_add_u32 s38, s38, s37
	s_addc_u32 s39, s39, 0
	global_load_dwordx4 v[150:153], v231, s[38:39] nt
	s_add_u32 s38, s38, s37
	s_addc_u32 s39, s39, 0
	global_load_dwordx4 v[154:157], v231, s[38:39] nt
	s_add_u32 s38, s38, s37
	s_addc_u32 s39, s39, 0
	global_load_dwordx4 v[158:161], v231, s[38:39] nt
	s_cmp_ge_u32 s100, s22
	s_cbranch_scc1 .Lwcm0_p1
	s_cmpk_ge_u32 s100, 0x900
	s_cbranch_scc1 .Lwcm0_t3_2
	s_cmpk_ge_u32 s100, 0x380
	s_cbranch_scc1 .Lwcm0_t2_2
	s_cmpk_ge_u32 s100, 0x280
	s_cbranch_scc1 .Lwcm0_t1_2
	s_movk_i32 s14, 0x78
	s_sub_u32 s99, s100, 0
	s_mul_i32 s44, s99, 0x66667
	s_lshr_b32 s44, s44, 24
	s_mul_i32 s36, s44, 40
	s_sub_u32 s99, s99, s36
	s_mul_i32 s38, s44, 0xa0000
	s_lshl_b32 s36, s99, 8
	s_add_u32 s38, s38, s36
	s_add_u32 s38, s38, 0x0
	s_lshl_b32 s36, s99, 6
	s_mov_b32 s32, 0x10000
	s_mul_i32 s36, s36, 0x800
	s_lshl_b32 s44, s44, 7
	s_add_u32 s36, s36, s44
	s_add_u32 s36, s36, 0x0
	s_mov_b32 s37, 0x28000
	s_movk_i32 s44, 0x800
	s_mov_b32 s99, 0x2800
	s_branch .Lwcm0_tj_2

.Lwcm0_tj_2:
	s_load_dwordx2 s[8:9], s[0:1], s14
	s_add_u32 s20, s12, s36
	s_addc_u32 s21, s13, 0
	v_mad_u32_u24 v231, v233, s99, v234
	v_writelane_b32 v237, s20, 12
	v_writelane_b32 v237, s21, 13
	v_writelane_b32 v237, s32, 14
	v_writelane_b32 v237, s44, 15
	s_add_u32 s100, s100, s23
	s_waitcnt lgkmcnt(0)
	s_add_u32 s38, s8, s38
	s_addc_u32 s39, s9, 0
	global_load_dwordx4 v[162:165], v231, s[38:39] nt
	s_add_u32 s38, s38, s37
	s_addc_u32 s39, s39, 0
	global_load_dwordx4 v[166:169], v231, s[38:39] nt
	s_add_u32 s38, s38, s37
	s_addc_u32 s39, s39, 0
	global_load_dwordx4 v[170:173], v231, s[38:39] nt
	s_add_u32 s38, s38, s37
	s_addc_u32 s39, s39, 0
	global_load_dwordx4 v[174:177], v231, s[38:39] nt
	s_cmp_ge_u32 s100, s22
	s_cbranch_scc1 .Lwcm0_p2
	s_cmpk_ge_u32 s100, 0x900
	s_cbranch_scc1 .Lwcm0_t3_3
	s_cmpk_ge_u32 s100, 0x380
	s_cbranch_scc1 .Lwcm0_t2_3
	s_cmpk_ge_u32 s100, 0x280
	s_cbranch_scc1 .Lwcm0_t1_3
	s_movk_i32 s14, 0x78
	s_sub_u32 s99, s100, 0
	s_mul_i32 s44, s99, 0x66667
	s_lshr_b32 s44, s44, 24
	s_mul_i32 s36, s44, 40
	s_sub_u32 s99, s99, s36
	s_mul_i32 s38, s44, 0xa0000
	s_lshl_b32 s36, s99, 8
	s_add_u32 s38, s38, s36
	s_add_u32 s38, s38, 0x0
	s_lshl_b32 s36, s99, 6
	s_mov_b32 s32, 0x10000
	s_mul_i32 s36, s36, 0x800
	s_lshl_b32 s44, s44, 7
	s_add_u32 s36, s36, s44
	s_add_u32 s36, s36, 0x0
	s_mov_b32 s37, 0x28000
	s_movk_i32 s44, 0x800
	s_mov_b32 s99, 0x2800
	s_branch .Lwcm0_tj_3

.Lwcm0_tj_3:
	s_load_dwordx2 s[8:9], s[0:1], s14
	s_add_u32 s20, s12, s36
	s_addc_u32 s21, s13, 0
	v_mad_u32_u24 v231, v233, s99, v234
	v_writelane_b32 v237, s20, 16
	v_writelane_b32 v237, s21, 17
	v_writelane_b32 v237, s32, 18
	v_writelane_b32 v237, s44, 19
	s_add_u32 s100, s100, s23
	s_waitcnt lgkmcnt(0)
	s_add_u32 s38, s8, s38
	s_addc_u32 s39, s9, 0
	global_load_dwordx4 v[178:181], v231, s[38:39] nt
	s_add_u32 s38, s38, s37
	s_addc_u32 s39, s39, 0
	global_load_dwordx4 v[182:185], v231, s[38:39] nt
	s_add_u32 s38, s38, s37
	s_addc_u32 s39, s39, 0
	global_load_dwordx4 v[186:189], v231, s[38:39] nt
	s_add_u32 s38, s38, s37
	s_addc_u32 s39, s39, 0
	global_load_dwordx4 v[190:193], v231, s[38:39] nt

.Lwcm0_tj_4:
	s_load_dwordx2 s[8:9], s[0:1], s14
	s_add_u32 s20, s12, s36
	s_addc_u32 s21, s13, 0
	v_mad_u32_u24 v231, v233, s99, v234
	v_writelane_b32 v237, s20, 8
	v_writelane_b32 v237, s21, 9
	v_writelane_b32 v237, s32, 10
	v_writelane_b32 v237, s44, 11
	s_add_u32 s100, s100, s23
	s_waitcnt lgkmcnt(0)
	s_add_u32 s38, s8, s38
	s_addc_u32 s39, s9, 0
	global_load_dwordx4 v[146:149], v231, s[38:39] nt
	s_add_u32 s38, s38, s37
	s_addc_u32 s39, s39, 0
	global_load_dwordx4 v[150:153], v231, s[38:39] nt
	s_add_u32 s38, s38, s37
	s_addc_u32 s39, s39, 0
	global_load_dwordx4 v[154:157], v231, s[38:39] nt
	s_add_u32 s38, s38, s37
	s_addc_u32 s39, s39, 0
	global_load_dwordx4 v[158:161], v231, s[38:39] nt
	s_waitcnt vmcnt(8)
	v_readlane_b32 s20, v237, 12
	v_readlane_b32 s21, v237, 13
	v_readlane_b32 s32, v237, 14
	v_readlane_b32 s35, v237, 15
	ds_write_b32 v226, v162 offset:0
	ds_write_b32 v226, v163 offset:4
	ds_write_b32 v226, v164 offset:8
	ds_write_b32 v226, v165 offset:12
	ds_write_b32 v226, v166 offset:4160
	ds_write_b32 v226, v167 offset:4164
	ds_write_b32 v226, v168 offset:4168
	ds_write_b32 v226, v169 offset:4172
	ds_write_b32 v226, v170 offset:8320
	ds_write_b32 v226, v171 offset:8324
	ds_write_b32 v226, v172 offset:8328
	ds_write_b32 v226, v173 offset:8332
	ds_write_b32 v226, v174 offset:12480
	ds_write_b32 v226, v175 offset:12484
	ds_write_b32 v226, v176 offset:12488
	ds_write_b32 v226, v177 offset:12492
	v_mad_u32_u24 v232, v235, s35, v236
	s_waitcnt lgkmcnt(0)
	s_barrier
	ds_read2_b32 v[162:163], v227 offset1:65
	ds_read2_b32 v[164:165], v227 offset0:130 offset1:195
	ds_read2_b32 v[166:167], v228 offset0:4 offset1:69
	ds_read2_b32 v[168:169], v228 offset0:134 offset1:199
	ds_read2_b32 v[170:171], v229 offset1:65
	ds_read2_b32 v[172:173], v229 offset0:130 offset1:195
	ds_read2_b32 v[174:175], v230 offset0:4 offset1:69
	ds_read2_b32 v[176:177], v230 offset0:134 offset1:199
	s_add_u32 s26, s20, s32
	s_addc_u32 s27, s21, 0
	s_waitcnt lgkmcnt(0)
	s_barrier
	v_cvt_pk_bf16_f32 v162, v162, v163
	v_cvt_pk_bf16_f32 v163, v164, v165
	v_cvt_pk_bf16_f32 v164, v166, v167
	v_cvt_pk_bf16_f32 v165, v168, v169
	v_cvt_pk_bf16_f32 v170, v170, v171
	v_cvt_pk_bf16_f32 v171, v172, v173
	v_cvt_pk_bf16_f32 v172, v174, v175
	v_cvt_pk_bf16_f32 v173, v176, v177
	global_store_dwordx4 v232, v[162:165], s[20:21]
	global_store_dwordx4 v232, v[170:173], s[26:27]
	s_cmp_ge_u32 s100, s22
	s_cbranch_scc1 .Lwcm0_tail1
	s_cmpk_ge_u32 s100, 0x900
	s_cbranch_scc1 .Lwcm0_t3_5
	s_cmpk_ge_u32 s100, 0x380
	s_cbranch_scc1 .Lwcm0_t2_5
	s_cmpk_ge_u32 s100, 0x280
	s_cbranch_scc1 .Lwcm0_t1_5
	s_movk_i32 s14, 0x78
	s_sub_u32 s99, s100, 0
	s_mul_i32 s44, s99, 0x66667
	s_lshr_b32 s44, s44, 24
	s_mul_i32 s36, s44, 40
	s_sub_u32 s99, s99, s36
	s_mul_i32 s38, s44, 0xa0000
	s_lshl_b32 s36, s99, 8
	s_add_u32 s38, s38, s36
	s_add_u32 s38, s38, 0x0
	s_lshl_b32 s36, s99, 6
	s_mov_b32 s32, 0x10000
	s_mul_i32 s36, s36, 0x800
	s_lshl_b32 s44, s44, 7
	s_add_u32 s36, s36, s44
	s_add_u32 s36, s36, 0x0
	s_mov_b32 s37, 0x28000
	s_movk_i32 s44, 0x800
	s_mov_b32 s99, 0x2800
	s_branch .Lwcm0_tj_5

.Lwcm0_tj_5:
	s_load_dwordx2 s[8:9], s[0:1], s14
	s_add_u32 s20, s12, s36
	s_addc_u32 s21, s13, 0
	v_mad_u32_u24 v231, v233, s99, v234
	v_writelane_b32 v237, s20, 12
	v_writelane_b32 v237, s21, 13
	v_writelane_b32 v237, s32, 14
	v_writelane_b32 v237, s44, 15
	s_add_u32 s100, s100, s23
	s_waitcnt lgkmcnt(0)
	s_add_u32 s38, s8, s38
	s_addc_u32 s39, s9, 0
	global_load_dwordx4 v[162:165], v231, s[38:39] nt
	s_add_u32 s38, s38, s37
	s_addc_u32 s39, s39, 0
	global_load_dwordx4 v[166:169], v231, s[38:39] nt
	s_add_u32 s38, s38, s37
	s_addc_u32 s39, s39, 0
	global_load_dwordx4 v[170:173], v231, s[38:39] nt
	s_add_u32 s38, s38, s37
	s_addc_u32 s39, s39, 0
	global_load_dwordx4 v[174:177], v231, s[38:39] nt
	s_waitcnt vmcnt(8)
	v_readlane_b32 s20, v237, 16
	v_readlane_b32 s21, v237, 17
	v_readlane_b32 s32, v237, 18
	v_readlane_b32 s35, v237, 19
	ds_write_b32 v226, v178 offset:0
	ds_write_b32 v226, v179 offset:4
	ds_write_b32 v226, v180 offset:8
	ds_write_b32 v226, v181 offset:12
	ds_write_b32 v226, v182 offset:4160
	ds_write_b32 v226, v183 offset:4164
	ds_write_b32 v226, v184 offset:4168
	ds_write_b32 v226, v185 offset:4172
	ds_write_b32 v226, v186 offset:8320
	ds_write_b32 v226, v187 offset:8324
	ds_write_b32 v226, v188 offset:8328
	ds_write_b32 v226, v189 offset:8332
	ds_write_b32 v226, v190 offset:12480
	ds_write_b32 v226, v191 offset:12484
	ds_write_b32 v226, v192 offset:12488
	ds_write_b32 v226, v193 offset:12492
	v_mad_u32_u24 v232, v235, s35, v236
	s_waitcnt lgkmcnt(0)
	s_barrier
	ds_read2_b32 v[178:179], v227 offset1:65
	ds_read2_b32 v[180:181], v227 offset0:130 offset1:195
	ds_read2_b32 v[182:183], v228 offset0:4 offset1:69
	ds_read2_b32 v[184:185], v228 offset0:134 offset1:199
	ds_read2_b32 v[186:187], v229 offset1:65
	ds_read2_b32 v[188:189], v229 offset0:130 offset1:195
	ds_read2_b32 v[190:191], v230 offset0:4 offset1:69
	ds_read2_b32 v[192:193], v230 offset0:134 offset1:199
	s_add_u32 s26, s20, s32
	s_addc_u32 s27, s21, 0
	s_waitcnt lgkmcnt(0)
	s_barrier
	v_cvt_pk_bf16_f32 v178, v178, v179
	v_cvt_pk_bf16_f32 v179, v180, v181
	v_cvt_pk_bf16_f32 v180, v182, v183
	v_cvt_pk_bf16_f32 v181, v184, v185
	v_cvt_pk_bf16_f32 v186, v186, v187
	v_cvt_pk_bf16_f32 v187, v188, v189
	v_cvt_pk_bf16_f32 v188, v190, v191
	v_cvt_pk_bf16_f32 v189, v192, v193
	global_store_dwordx4 v232, v[178:181], s[20:21]
	global_store_dwordx4 v232, v[186:189], s[26:27]
	s_cmp_ge_u32 s100, s22
	s_cbranch_scc1 .Lwcm0_tail2
	s_cmpk_ge_u32 s100, 0x900
	s_cbranch_scc1 .Lwcm0_t3_6
	s_cmpk_ge_u32 s100, 0x380
	s_cbranch_scc1 .Lwcm0_t2_6
	s_cmpk_ge_u32 s100, 0x280
	s_cbranch_scc1 .Lwcm0_t1_6
	s_movk_i32 s14, 0x78
	s_sub_u32 s99, s100, 0
	s_mul_i32 s44, s99, 0x66667
	s_lshr_b32 s44, s44, 24
	s_mul_i32 s36, s44, 40
	s_sub_u32 s99, s99, s36
	s_mul_i32 s38, s44, 0xa0000
	s_lshl_b32 s36, s99, 8
	s_add_u32 s38, s38, s36
	s_add_u32 s38, s38, 0x0
	s_lshl_b32 s36, s99, 6
	s_mov_b32 s32, 0x10000
	s_mul_i32 s36, s36, 0x800
	s_lshl_b32 s44, s44, 7
	s_add_u32 s36, s36, s44
	s_add_u32 s36, s36, 0x0
	s_mov_b32 s37, 0x28000
	s_movk_i32 s44, 0x800
	s_mov_b32 s99, 0x2800
	s_branch .Lwcm0_tj_6

.Lwcm0_tj_6:
	s_load_dwordx2 s[8:9], s[0:1], s14
	s_add_u32 s20, s12, s36
	s_addc_u32 s21, s13, 0
	v_mad_u32_u24 v231, v233, s99, v234
	v_writelane_b32 v237, s20, 16
	v_writelane_b32 v237, s21, 17
	v_writelane_b32 v237, s32, 18
	v_writelane_b32 v237, s44, 19
	s_add_u32 s100, s100, s23
	s_waitcnt lgkmcnt(0)
	s_add_u32 s38, s8, s38
	s_addc_u32 s39, s9, 0
	global_load_dwordx4 v[178:181], v231, s[38:39] nt
	s_add_u32 s38, s38, s37
	s_addc_u32 s39, s39, 0
	global_load_dwordx4 v[182:185], v231, s[38:39] nt
	s_add_u32 s38, s38, s37
	s_addc_u32 s39, s39, 0
	global_load_dwordx4 v[186:189], v231, s[38:39] nt
	s_add_u32 s38, s38, s37
	s_addc_u32 s39, s39, 0
	global_load_dwordx4 v[190:193], v231, s[38:39] nt
	s_branch .Lwcm0_loop

.Lwcm1_tj_1:
	s_load_dwordx2 s[8:9], s[0:1], s14
	s_add_u32 s20, s12, s36
	s_addc_u32 s21, s13, 0
	v_mad_u32_u24 v231, v233, s99, v234
	v_writelane_b32 v237, s20, 8
	v_writelane_b32 v237, s21, 9
	v_writelane_b32 v237, s32, 10
	v_writelane_b32 v237, s44, 11
	s_add_u32 s100, s100, s23
	s_waitcnt lgkmcnt(0)
	s_add_u32 s38, s8, s38
	s_addc_u32 s39, s9, 0
	global_load_dwordx4 v[146:149], v231, s[38:39] nt
	s_add_u32 s38, s38, s37
	s_addc_u32 s39, s39, 0
	global_load_dwordx4 v[150:153], v231, s[38:39] nt
	s_add_u32 s38, s38, s37
	s_addc_u32 s39, s39, 0
	global_load_dwordx4 v[154:157], v231, s[38:39] nt
	s_add_u32 s38, s38, s37
	s_addc_u32 s39, s39, 0
	global_load_dwordx4 v[158:161], v231, s[38:39] nt
	s_cmp_ge_u32 s100, s22
	s_cbranch_scc1 .Lwcm1_p1
	s_cmpk_ge_u32 s100, 0x900
	s_cbranch_scc1 .Lwcm1_t3_2
	s_cmpk_ge_u32 s100, 0x380
	s_cbranch_scc1 .Lwcm1_t2_2
	s_cmpk_ge_u32 s100, 0x280
	s_cbranch_scc1 .Lwcm1_t1_2
	s_movk_i32 s14, 0x78
	s_sub_u32 s99, s100, 0
	s_mul_i32 s44, s99, 0x66667
	s_lshr_b32 s44, s44, 24
	s_mul_i32 s36, s44, 40
	s_sub_u32 s99, s99, s36
	s_mul_i32 s38, s44, 0xa0000
	s_lshl_b32 s36, s99, 8
	s_add_u32 s38, s38, s36
	s_add_u32 s38, s38, 0xa00000
	s_lshl_b32 s36, s99, 6
	s_mov_b32 s32, 0x10000
	s_mul_i32 s36, s36, 0x800
	s_lshl_b32 s44, s44, 7
	s_add_u32 s36, s36, s44
	s_add_u32 s36, s36, 0x500000
	s_mov_b32 s37, 0x28000
	s_movk_i32 s44, 0x800
	s_mov_b32 s99, 0x2800
	s_branch .Lwcm1_tj_2

.Lwcm1_tj_2:
	s_load_dwordx2 s[8:9], s[0:1], s14
	s_add_u32 s20, s12, s36
	s_addc_u32 s21, s13, 0
	v_mad_u32_u24 v231, v233, s99, v234
	v_writelane_b32 v237, s20, 12
	v_writelane_b32 v237, s21, 13
	v_writelane_b32 v237, s32, 14
	v_writelane_b32 v237, s44, 15
	s_add_u32 s100, s100, s23
	s_waitcnt lgkmcnt(0)
	s_add_u32 s38, s8, s38
	s_addc_u32 s39, s9, 0
	global_load_dwordx4 v[162:165], v231, s[38:39] nt
	s_add_u32 s38, s38, s37
	s_addc_u32 s39, s39, 0
	global_load_dwordx4 v[166:169], v231, s[38:39] nt
	s_add_u32 s38, s38, s37
	s_addc_u32 s39, s39, 0
	global_load_dwordx4 v[170:173], v231, s[38:39] nt
	s_add_u32 s38, s38, s37
	s_addc_u32 s39, s39, 0
	global_load_dwordx4 v[174:177], v231, s[38:39] nt
	s_cmp_ge_u32 s100, s22
	s_cbranch_scc1 .Lwcm1_p2
	s_cmpk_ge_u32 s100, 0x900
	s_cbranch_scc1 .Lwcm1_t3_3
	s_cmpk_ge_u32 s100, 0x380
	s_cbranch_scc1 .Lwcm1_t2_3
	s_cmpk_ge_u32 s100, 0x280
	s_cbranch_scc1 .Lwcm1_t1_3
	s_movk_i32 s14, 0x78
	s_sub_u32 s99, s100, 0
	s_mul_i32 s44, s99, 0x66667
	s_lshr_b32 s44, s44, 24
	s_mul_i32 s36, s44, 40
	s_sub_u32 s99, s99, s36
	s_mul_i32 s38, s44, 0xa0000
	s_lshl_b32 s36, s99, 8
	s_add_u32 s38, s38, s36
	s_add_u32 s38, s38, 0xa00000
	s_lshl_b32 s36, s99, 6
	s_mov_b32 s32, 0x10000
	s_mul_i32 s36, s36, 0x800
	s_lshl_b32 s44, s44, 7
	s_add_u32 s36, s36, s44
	s_add_u32 s36, s36, 0x500000
	s_mov_b32 s37, 0x28000
	s_movk_i32 s44, 0x800
	s_mov_b32 s99, 0x2800
	s_branch .Lwcm1_tj_3

.Lwcm1_tj_4:
	s_load_dwordx2 s[8:9], s[0:1], s14
	s_add_u32 s20, s12, s36
	s_addc_u32 s21, s13, 0
	v_mad_u32_u24 v231, v233, s99, v234
	v_writelane_b32 v237, s20, 8
	v_writelane_b32 v237, s21, 9
	v_writelane_b32 v237, s32, 10
	v_writelane_b32 v237, s44, 11
	s_add_u32 s100, s100, s23
	s_waitcnt lgkmcnt(0)
	s_add_u32 s38, s8, s38
	s_addc_u32 s39, s9, 0
	global_load_dwordx4 v[146:149], v231, s[38:39] nt
	s_add_u32 s38, s38, s37
	s_addc_u32 s39, s39, 0
	global_load_dwordx4 v[150:153], v231, s[38:39] nt
	s_add_u32 s38, s38, s37
	s_addc_u32 s39, s39, 0
	global_load_dwordx4 v[154:157], v231, s[38:39] nt
	s_add_u32 s38, s38, s37
	s_addc_u32 s39, s39, 0
	global_load_dwordx4 v[158:161], v231, s[38:39] nt
	s_waitcnt vmcnt(8)
	v_readlane_b32 s20, v237, 12
	v_readlane_b32 s21, v237, 13
	v_readlane_b32 s32, v237, 14
	v_readlane_b32 s35, v237, 15
	ds_write_b32 v226, v162 offset:0
	ds_write_b32 v226, v163 offset:4
	ds_write_b32 v226, v164 offset:8
	ds_write_b32 v226, v165 offset:12
	ds_write_b32 v226, v166 offset:4160
	ds_write_b32 v226, v167 offset:4164
	ds_write_b32 v226, v168 offset:4168
	ds_write_b32 v226, v169 offset:4172
	ds_write_b32 v226, v170 offset:8320
	ds_write_b32 v226, v171 offset:8324
	ds_write_b32 v226, v172 offset:8328
	ds_write_b32 v226, v173 offset:8332
	ds_write_b32 v226, v174 offset:12480
	ds_write_b32 v226, v175 offset:12484
	ds_write_b32 v226, v176 offset:12488
	ds_write_b32 v226, v177 offset:12492
	v_mad_u32_u24 v232, v235, s35, v236
	s_waitcnt lgkmcnt(0)
	s_barrier
	ds_read2_b32 v[162:163], v227 offset1:65
	ds_read2_b32 v[164:165], v227 offset0:130 offset1:195
	ds_read2_b32 v[166:167], v228 offset0:4 offset1:69
	ds_read2_b32 v[168:169], v228 offset0:134 offset1:199
	ds_read2_b32 v[170:171], v229 offset1:65
	ds_read2_b32 v[172:173], v229 offset0:130 offset1:195
	ds_read2_b32 v[174:175], v230 offset0:4 offset1:69
	ds_read2_b32 v[176:177], v230 offset0:134 offset1:199
	s_add_u32 s26, s20, s32
	s_addc_u32 s27, s21, 0
	s_waitcnt lgkmcnt(0)
	s_barrier
	v_cvt_pk_bf16_f32 v162, v162, v163
	v_cvt_pk_bf16_f32 v163, v164, v165
	v_cvt_pk_bf16_f32 v164, v166, v167
	v_cvt_pk_bf16_f32 v165, v168, v169
	v_cvt_pk_bf16_f32 v170, v170, v171
	v_cvt_pk_bf16_f32 v171, v172, v173
	v_cvt_pk_bf16_f32 v172, v174, v175
	v_cvt_pk_bf16_f32 v173, v176, v177
	global_store_dwordx4 v232, v[162:165], s[20:21]
	global_store_dwordx4 v232, v[170:173], s[26:27]
	s_cmp_ge_u32 s100, s22
	s_cbranch_scc1 .Lwcm1_tail1
	s_cmpk_ge_u32 s100, 0x900
	s_cbranch_scc1 .Lwcm1_t3_5
	s_cmpk_ge_u32 s100, 0x380
	s_cbranch_scc1 .Lwcm1_t2_5
	s_cmpk_ge_u32 s100, 0x280
	s_cbranch_scc1 .Lwcm1_t1_5
	s_movk_i32 s14, 0x78
	s_sub_u32 s99, s100, 0
	s_mul_i32 s44, s99, 0x66667
	s_lshr_b32 s44, s44, 24
	s_mul_i32 s36, s44, 40
	s_sub_u32 s99, s99, s36
	s_mul_i32 s38, s44, 0xa0000
	s_lshl_b32 s36, s99, 8
	s_add_u32 s38, s38, s36
	s_add_u32 s38, s38, 0xa00000
	s_lshl_b32 s36, s99, 6
	s_mov_b32 s32, 0x10000
	s_mul_i32 s36, s36, 0x800
	s_lshl_b32 s44, s44, 7
	s_add_u32 s36, s36, s44
	s_add_u32 s36, s36, 0x500000
	s_mov_b32 s37, 0x28000
	s_movk_i32 s44, 0x800
	s_mov_b32 s99, 0x2800
	s_branch .Lwcm1_tj_5

.Lwcm1_tj_5:
	s_load_dwordx2 s[8:9], s[0:1], s14
	s_add_u32 s20, s12, s36
	s_addc_u32 s21, s13, 0
	v_mad_u32_u24 v231, v233, s99, v234
	v_writelane_b32 v237, s20, 12
	v_writelane_b32 v237, s21, 13
	v_writelane_b32 v237, s32, 14
	v_writelane_b32 v237, s44, 15
	s_add_u32 s100, s100, s23
	s_waitcnt lgkmcnt(0)
	s_add_u32 s38, s8, s38
	s_addc_u32 s39, s9, 0
	global_load_dwordx4 v[162:165], v231, s[38:39] nt
	s_add_u32 s38, s38, s37
	s_addc_u32 s39, s39, 0
	global_load_dwordx4 v[166:169], v231, s[38:39] nt
	s_add_u32 s38, s38, s37
	s_addc_u32 s39, s39, 0
	global_load_dwordx4 v[170:173], v231, s[38:39] nt
	s_add_u32 s38, s38, s37
	s_addc_u32 s39, s39, 0
	global_load_dwordx4 v[174:177], v231, s[38:39] nt
	s_waitcnt vmcnt(8)
	v_readlane_b32 s20, v237, 16
	v_readlane_b32 s21, v237, 17
	v_readlane_b32 s32, v237, 18
	v_readlane_b32 s35, v237, 19
	ds_write_b32 v226, v178 offset:0
	ds_write_b32 v226, v179 offset:4
	ds_write_b32 v226, v180 offset:8
	ds_write_b32 v226, v181 offset:12
	ds_write_b32 v226, v182 offset:4160
	ds_write_b32 v226, v183 offset:4164
	ds_write_b32 v226, v184 offset:4168
	ds_write_b32 v226, v185 offset:4172
	ds_write_b32 v226, v186 offset:8320
	ds_write_b32 v226, v187 offset:8324
	ds_write_b32 v226, v188 offset:8328
	ds_write_b32 v226, v189 offset:8332
	ds_write_b32 v226, v190 offset:12480
	ds_write_b32 v226, v191 offset:12484
	ds_write_b32 v226, v192 offset:12488
	ds_write_b32 v226, v193 offset:12492
	v_mad_u32_u24 v232, v235, s35, v236
	s_waitcnt lgkmcnt(0)
	s_barrier
	ds_read2_b32 v[178:179], v227 offset1:65
	ds_read2_b32 v[180:181], v227 offset0:130 offset1:195
	ds_read2_b32 v[182:183], v228 offset0:4 offset1:69
	ds_read2_b32 v[184:185], v228 offset0:134 offset1:199
	ds_read2_b32 v[186:187], v229 offset1:65
	ds_read2_b32 v[188:189], v229 offset0:130 offset1:195
	ds_read2_b32 v[190:191], v230 offset0:4 offset1:69
	ds_read2_b32 v[192:193], v230 offset0:134 offset1:199
	s_add_u32 s26, s20, s32
	s_addc_u32 s27, s21, 0
	s_waitcnt lgkmcnt(0)
	s_barrier
	v_cvt_pk_bf16_f32 v178, v178, v179
	v_cvt_pk_bf16_f32 v179, v180, v181
	v_cvt_pk_bf16_f32 v180, v182, v183
	v_cvt_pk_bf16_f32 v181, v184, v185
	v_cvt_pk_bf16_f32 v186, v186, v187
	v_cvt_pk_bf16_f32 v187, v188, v189
	v_cvt_pk_bf16_f32 v188, v190, v191
	v_cvt_pk_bf16_f32 v189, v192, v193
	global_store_dwordx4 v232, v[178:181], s[20:21]
	global_store_dwordx4 v232, v[186:189], s[26:27]
	s_cmp_ge_u32 s100, s22
	s_cbranch_scc1 .Lwcm1_tail2
	s_cmpk_ge_u32 s100, 0x900
	s_cbranch_scc1 .Lwcm1_t3_6
	s_cmpk_ge_u32 s100, 0x380
	s_cbranch_scc1 .Lwcm1_t2_6
	s_cmpk_ge_u32 s100, 0x280
	s_cbranch_scc1 .Lwcm1_t1_6
	s_movk_i32 s14, 0x78
	s_sub_u32 s99, s100, 0
	s_mul_i32 s44, s99, 0x66667
	s_lshr_b32 s44, s44, 24
	s_mul_i32 s36, s44, 40
	s_sub_u32 s99, s99, s36
	s_mul_i32 s38, s44, 0xa0000
	s_lshl_b32 s36, s99, 8
	s_add_u32 s38, s38, s36
	s_add_u32 s38, s38, 0xa00000
	s_lshl_b32 s36, s99, 6
	s_mov_b32 s32, 0x10000
	s_mul_i32 s36, s36, 0x800
	s_lshl_b32 s44, s44, 7
	s_add_u32 s36, s36, s44
	s_add_u32 s36, s36, 0x500000
	s_mov_b32 s37, 0x28000
	s_movk_i32 s44, 0x800
	s_mov_b32 s99, 0x2800
	s_branch .Lwcm1_tj_6

.Lxbi4_skip:
	s_barrier
	s_nop 0
	v_ashrrev_i32_e32 v1, 6, v0
	s_waitcnt vmcnt(7)
	v_lshl_add_u32 v4, s0, 2, v1
	s_movk_i32 s0, 0x2800
	v_cmp_gt_i32_e32 vcc, s0, v4
	s_and_saveexec_b64 s[0:1], vcc
	s_cbranch_execz .LBB0_1033
	s_waitcnt vmcnt(0) lgkmcnt(0)
	v_readfirstlane_b32 s2, v4
	v_readlane_b32 s4, v242, 42
	v_readlane_b32 s5, v242, 43
	v_readlane_b32 s6, v242, 3
	v_readlane_b32 s7, v242, 4
	s_load_dword s3, s[4:5], 0x0
	s_sub_u32 s20, s4, 0x118
	s_subb_u32 s21, s5, 0
	s_load_dwordx2 s[22:23], s[20:21], 0xe0
	s_load_dwordx2 s[24:25], s[20:21], 0xe8
	v_and_b32_e32 v11, 63, v137
	v_lshrrev_b32_e32 v9, 4, v11
	v_and_b32_e32 v11, 15, v11
	v_lshlrev_b32_e32 v11, 2, v11
	v_lshl_add_u32 v5, v9, 6, v11
	v_and_b32_e32 v10, 1, v9
	v_add_u32_e32 v10, 4, v10
	v_lshl_add_u32 v7, v10, 6, v11
	v_lshlrev_b32_e32 v6, 2, v5
	v_lshlrev_b32_e32 v8, 2, v7
	v_lshlrev_b32_e32 v5, 1, v5
	v_lshlrev_b32_e32 v7, 1, v7
	v_lshlrev_b32_e32 v9, 2, v9
	v_lshlrev_b32_e32 v10, 2, v10
	v_mov_b32_e32 v126, 0x3a27c5ac
	v_mov_b32_e32 v127, 0x3c800000
	s_add_u32 s8, s6, 0xddc8100
	s_addc_u32 s9, s7, 0
	s_add_u32 s10, s6, 0xe548100
	s_addc_u32 s11, s7, 0
	s_add_u32 s12, s6, 0xd5f8100
	s_addc_u32 s13, s7, 0
	s_add_u32 s14, s6, 0x5b78d00
	s_addc_u32 s15, s7, 0
	s_add_u32 s16, s6, 0xdd78100
	s_addc_u32 s17, s7, 0
	s_add_u32 s18, s6, 0x30f8600
	s_addc_u32 s19, s7, 0
	s_waitcnt lgkmcnt(0)
	s_lshl_b32 s3, s3, 2
	global_load_dwordx4 v[12:15], v6, s[22:23]
	global_load_dwordx4 v[16:19], v8, s[22:23]
	global_load_dwordx4 v[20:23], v6, s[24:25]
	global_load_dwordx4 v[24:27], v8, s[24:25]
	s_mul_i32 s4, s2, 0x300
	s_add_u32 s20, s8, s4
	s_addc_u32 s21, s9, 0
	s_add_u32 s22, s10, s4
	s_addc_u32 s23, s11, 0
	s_add_u32 s24, s12, s4
	s_addc_u32 s25, s13, 0
	s_mul_i32 s4, s2, 0x1600
	s_add_u32 s26, s14, s4
	s_addc_u32 s27, s15, 0
	s_lshl_b32 s4, s2, 5
	s_add_u32 s28, s16, s4
	s_addc_u32 s29, s17, 0
	global_load_dwordx2 v[28:29], v5, s[20:21] nt
	global_load_dwordx2 v[30:31], v5, s[22:23] nt
	global_load_dwordx2 v[32:33], v5, s[24:25] nt
	global_load_dwordx4 v[34:37], v6, s[26:27] nt
	global_load_dword v38, v9, s[28:29] nt
	global_load_dwordx2 v[40:41], v7, s[20:21] nt
	global_load_dwordx2 v[42:43], v7, s[22:23] nt
	global_load_dwordx2 v[44:45], v7, s[24:25] nt
	global_load_dwordx4 v[46:49], v8, s[26:27] nt
	global_load_dword v50, v10, s[28:29] nt
	s_waitcnt vmcnt(0)
.Lpo0_loop:
	s_lshl_b32 s4, s2, 11
	s_add_u32 s40, s18, s4
	s_addc_u32 s41, s19, 0
	s_add_i32 s2, s2, s3
	s_cmp_lt_u32 s2, 0x2800
	s_cbranch_scc0 .Lpo0_last0
	s_mul_i32 s4, s2, 0x300
	s_add_u32 s30, s8, s4
	s_addc_u32 s31, s9, 0
	s_add_u32 s32, s10, s4
	s_addc_u32 s33, s11, 0
	s_add_u32 s34, s12, s4
	s_addc_u32 s35, s13, 0
	s_mul_i32 s4, s2, 0x1600
	s_add_u32 s36, s14, s4
	s_addc_u32 s37, s15, 0
	s_lshl_b32 s4, s2, 5
	s_add_u32 s38, s16, s4
	s_addc_u32 s39, s17, 0
	global_load_dwordx2 v[76:77], v5, s[30:31] nt
	global_load_dwordx2 v[78:79], v5, s[32:33] nt
	global_load_dwordx2 v[80:81], v5, s[34:35] nt
	global_load_dwordx4 v[82:85], v6, s[36:37] nt
	global_load_dword v86, v9, s[38:39] nt
	global_load_dwordx2 v[88:89], v7, s[30:31] nt
	global_load_dwordx2 v[90:91], v7, s[32:33] nt
	global_load_dwordx2 v[92:93], v7, s[34:35] nt
	global_load_dwordx4 v[94:97], v8, s[36:37] nt
	global_load_dword v98, v10, s[38:39] nt
	s_waitcnt vmcnt(12)
	s_branch .Lpo0_go0

.Lpo0_go0:
	v_lshlrev_b32_e32 v100, 16, v28
	v_and_b32_e32 v101, 0xffff0000, v28
	v_lshlrev_b32_e32 v110, 16, v30
	v_and_b32_e32 v111, 0xffff0000, v30
	v_lshlrev_b32_e32 v102, 16, v29
	v_and_b32_e32 v103, 0xffff0000, v29
	v_lshlrev_b32_e32 v112, 16, v31
	v_and_b32_e32 v113, 0xffff0000, v31
	v_add_f32_e32 v100, v100, v110
	v_add_f32_e32 v101, v101, v111
	v_add_f32_e32 v102, v102, v112
	v_add_f32_e32 v103, v103, v113
	v_lshlrev_b32_e32 v104, 16, v40
	v_and_b32_e32 v105, 0xffff0000, v40
	v_lshlrev_b32_e32 v114, 16, v42
	v_and_b32_e32 v115, 0xffff0000, v42
	v_lshlrev_b32_e32 v106, 16, v41
	v_and_b32_e32 v107, 0xffff0000, v41
	v_lshlrev_b32_e32 v116, 16, v43
	v_and_b32_e32 v117, 0xffff0000, v43
	v_add_f32_e32 v104, v104, v114
	v_add_f32_e32 v105, v105, v115
	v_add_f32_e32 v106, v106, v116
	v_add_f32_e32 v107, v107, v117
	v_add_f32_e32 v108, v100, v101
	v_add_f32_e32 v110, v102, v103
	v_add_f32_e32 v109, v104, v105
	v_add_f32_e32 v114, v106, v107
	v_add_f32_e32 v108, v108, v110
	v_add_f32_e32 v109, v109, v114
	s_nop 0
	v_add_f32_dpp v108, v108, v108 quad_perm:[1,0,3,2] row_mask:0xf bank_mask:0xf bound_ctrl:1
	v_add_f32_dpp v109, v109, v109 quad_perm:[1,0,3,2] row_mask:0xf bank_mask:0xf bound_ctrl:1
	v_lshlrev_b32_e32 v118, 16, v32
	v_add_f32_dpp v108, v108, v108 quad_perm:[2,3,0,1] row_mask:0xf bank_mask:0xf bound_ctrl:1
	v_add_f32_dpp v109, v109, v109 quad_perm:[2,3,0,1] row_mask:0xf bank_mask:0xf bound_ctrl:1
	v_and_b32_e32 v119, 0xffff0000, v32
	v_add_f32_dpp v108, v108, v108 row_ror:4 row_mask:0xf bank_mask:0xf bound_ctrl:1
	v_add_f32_dpp v109, v109, v109 row_ror:4 row_mask:0xf bank_mask:0xf bound_ctrl:1
	v_lshlrev_b32_e32 v120, 16, v33
	v_add_f32_dpp v108, v108, v108 row_ror:8 row_mask:0xf bank_mask:0xf bound_ctrl:1
	v_add_f32_dpp v109, v109, v109 row_ror:8 row_mask:0xf bank_mask:0xf bound_ctrl:1
	v_and_b32_e32 v121, 0xffff0000, v33
	v_lshlrev_b32_e32 v122, 16, v44
	v_mul_f32_e32 v108, v108, v127
	v_mul_f32_e32 v109, v109, v127
	v_sub_f32_e32 v100, v100, v108
	v_sub_f32_e32 v101, v101, v108
	v_sub_f32_e32 v102, v102, v108
	v_sub_f32_e32 v103, v103, v108
	v_sub_f32_e32 v104, v104, v109
	v_sub_f32_e32 v105, v105, v109
	v_sub_f32_e32 v106, v106, v109
	v_sub_f32_e32 v107, v107, v109
	v_mul_f32_e32 v108, v100, v100
	v_mul_f32_e32 v109, v104, v104
	v_fmac_f32_e32 v108, v101, v101
	v_fmac_f32_e32 v109, v105, v105
	v_fmac_f32_e32 v108, v102, v102
	v_fmac_f32_e32 v109, v106, v106
	v_fmac_f32_e32 v108, v103, v103
	v_fmac_f32_e32 v109, v107, v107
	s_nop 0
	v_add_f32_dpp v108, v108, v108 quad_perm:[1,0,3,2] row_mask:0xf bank_mask:0xf bound_ctrl:1
	v_add_f32_dpp v109, v109, v109 quad_perm:[1,0,3,2] row_mask:0xf bank_mask:0xf bound_ctrl:1
	v_and_b32_e32 v123, 0xffff0000, v44
	v_add_f32_dpp v108, v108, v108 quad_perm:[2,3,0,1] row_mask:0xf bank_mask:0xf bound_ctrl:1
	v_add_f32_dpp v109, v109, v109 quad_perm:[2,3,0,1] row_mask:0xf bank_mask:0xf bound_ctrl:1
	v_lshlrev_b32_e32 v124, 16, v45
	v_add_f32_dpp v108, v108, v108 row_ror:4 row_mask:0xf bank_mask:0xf bound_ctrl:1
	v_add_f32_dpp v109, v109, v109 row_ror:4 row_mask:0xf bank_mask:0xf bound_ctrl:1
	v_and_b32_e32 v125, 0xffff0000, v45
	v_add_f32_dpp v108, v108, v108 row_ror:8 row_mask:0xf bank_mask:0xf bound_ctrl:1
	v_add_f32_dpp v109, v109, v109 row_ror:8 row_mask:0xf bank_mask:0xf bound_ctrl:1
	s_nop 0
	v_fma_f32 v108, v108, v127, v126
	v_fma_f32 v109, v109, v127, v126
	v_rsq_f32_e32 v108, v108
	v_rsq_f32_e32 v109, v109
	v_fma_f32 v110, v38, v34, v20
	v_fma_f32 v111, v38, v35, v21
	v_fma_f32 v112, v38, v36, v22
	v_fma_f32 v113, v38, v37, v23
	v_fma_f32 v114, v50, v46, v24
	v_fma_f32 v115, v50, v47, v25
	v_fma_f32 v116, v50, v48, v26
	v_fma_f32 v117, v50, v49, v27
	v_mul_f32_e32 v100, v100, v108
	v_mul_f32_e32 v101, v101, v108
	v_mul_f32_e32 v102, v102, v108
	v_mul_f32_e32 v103, v103, v108
	v_mul_f32_e32 v104, v104, v109
	v_mul_f32_e32 v105, v105, v109
	v_mul_f32_e32 v106, v106, v109
	v_mul_f32_e32 v107, v107, v109
	v_fmac_f32_e32 v110, v100, v12
	v_fmac_f32_e32 v111, v101, v13
	v_fmac_f32_e32 v112, v102, v14
	v_fmac_f32_e32 v113, v103, v15
	v_fmac_f32_e32 v114, v104, v16
	v_fmac_f32_e32 v115, v105, v17
	v_fmac_f32_e32 v116, v106, v18
	v_fmac_f32_e32 v117, v107, v19
	v_mul_f32_e32 v110, v110, v118
	v_mul_f32_e32 v111, v111, v119
	v_mul_f32_e32 v112, v112, v120
	v_mul_f32_e32 v113, v113, v121
	v_mul_f32_e32 v114, v114, v122
	v_mul_f32_e32 v115, v115, v123
	v_mul_f32_e32 v116, v116, v124
	v_mul_f32_e32 v117, v117, v125
	v_cvt_pk_bf16_f32 v110, v110, v111
	v_cvt_pk_bf16_f32 v111, v112, v113
	v_cvt_pk_bf16_f32 v114, v114, v115
	v_cvt_pk_bf16_f32 v115, v116, v117
	global_store_dwordx2 v5, v[110:111], s[40:41]
	global_store_dwordx2 v7, v[114:115], s[40:41]
	s_cmp_lt_u32 s2, 0x2800
	s_cbranch_scc0 .Lpo0_done
	s_lshl_b32 s4, s2, 11
	s_add_u32 s40, s18, s4
	s_addc_u32 s41, s19, 0
	s_add_i32 s2, s2, s3
	s_cmp_lt_u32 s2, 0x2800
	s_cbranch_scc0 .Lpo0_last1
	s_mul_i32 s4, s2, 0x300
	s_add_u32 s20, s8, s4
	s_addc_u32 s21, s9, 0
	s_add_u32 s22, s10, s4
	s_addc_u32 s23, s11, 0
	s_add_u32 s24, s12, s4
	s_addc_u32 s25, s13, 0
	s_mul_i32 s4, s2, 0x1600
	s_add_u32 s26, s14, s4
	s_addc_u32 s27, s15, 0
	s_lshl_b32 s4, s2, 5
	s_add_u32 s28, s16, s4
	s_addc_u32 s29, s17, 0
	global_load_dwordx2 v[28:29], v5, s[20:21] nt
	global_load_dwordx2 v[30:31], v5, s[22:23] nt
	global_load_dwordx2 v[32:33], v5, s[24:25] nt
	global_load_dwordx4 v[34:37], v6, s[26:27] nt
	global_load_dword v38, v9, s[28:29] nt
	global_load_dwordx2 v[40:41], v7, s[20:21] nt
	global_load_dwordx2 v[42:43], v7, s[22:23] nt
	global_load_dwordx2 v[44:45], v7, s[24:25] nt
	global_load_dwordx4 v[46:49], v8, s[26:27] nt
	global_load_dword v50, v10, s[28:29] nt
	s_waitcnt vmcnt(12)
	s_branch .Lpo0_go1

.Lxbi13_skip:
	s_barrier
	s_nop 0
	v_ashrrev_i32_e32 v1, 6, v0
	s_waitcnt vmcnt(7)
	v_lshl_add_u32 v4, s0, 2, v1
	s_movk_i32 s0, 0x2800
	v_cmp_gt_i32_e32 vcc, s0, v4
	s_and_saveexec_b64 s[0:1], vcc
	s_cbranch_execz .LBB0_2031
	s_waitcnt vmcnt(0) lgkmcnt(0)
	v_readfirstlane_b32 s2, v4
	v_readlane_b32 s4, v242, 42
	v_readlane_b32 s5, v242, 43
	v_readlane_b32 s6, v242, 3
	v_readlane_b32 s7, v242, 4
	s_load_dword s3, s[4:5], 0x0
	s_sub_u32 s20, s4, 0x118
	s_subb_u32 s21, s5, 0
	s_load_dwordx2 s[22:23], s[20:21], 0xe0
	s_load_dwordx2 s[24:25], s[20:21], 0xe8
	v_and_b32_e32 v11, 63, v137
	v_lshrrev_b32_e32 v9, 4, v11
	v_and_b32_e32 v11, 15, v11
	v_lshlrev_b32_e32 v11, 2, v11
	v_lshl_add_u32 v5, v9, 6, v11
	v_and_b32_e32 v10, 1, v9
	v_add_u32_e32 v10, 4, v10
	v_lshl_add_u32 v7, v10, 6, v11
	v_lshlrev_b32_e32 v6, 2, v5
	v_lshlrev_b32_e32 v8, 2, v7
	v_lshlrev_b32_e32 v5, 1, v5
	v_lshlrev_b32_e32 v7, 1, v7
	v_lshlrev_b32_e32 v9, 2, v9
	v_lshlrev_b32_e32 v10, 2, v10
	v_mov_b32_e32 v126, 0x3a27c5ac
	v_mov_b32_e32 v127, 0x3c800000
	s_add_u32 s8, s6, 0xddc8100
	s_addc_u32 s9, s7, 0
	s_add_u32 s10, s6, 0xe548100
	s_addc_u32 s11, s7, 0
	s_add_u32 s12, s6, 0xd5f8100
	s_addc_u32 s13, s7, 0
	s_add_u32 s14, s6, 0x5b78d00
	s_addc_u32 s15, s7, 0
	s_add_u32 s16, s6, 0xdd78100
	s_addc_u32 s17, s7, 0
	s_add_u32 s18, s6, 0x30f8600
	s_addc_u32 s19, s7, 0
	s_waitcnt lgkmcnt(0)
	s_lshl_b32 s3, s3, 2
	s_add_u32 s22, s22, 0x600
	s_addc_u32 s23, s23, 0
	s_add_u32 s24, s24, 0x600
	s_addc_u32 s25, s25, 0
	global_load_dwordx4 v[12:15], v6, s[22:23]
	global_load_dwordx4 v[16:19], v8, s[22:23]
	global_load_dwordx4 v[20:23], v6, s[24:25]
	global_load_dwordx4 v[24:27], v8, s[24:25]
	s_mul_i32 s4, s2, 0x300
	s_add_u32 s20, s8, s4
	s_addc_u32 s21, s9, 0
	s_add_u32 s22, s10, s4
	s_addc_u32 s23, s11, 0
	s_add_u32 s24, s12, s4
	s_addc_u32 s25, s13, 0
	s_mul_i32 s4, s2, 0x1600
	s_add_u32 s26, s14, s4
	s_addc_u32 s27, s15, 0
	s_lshl_b32 s4, s2, 5
	s_add_u32 s28, s16, s4
	s_addc_u32 s29, s17, 0
	global_load_dwordx2 v[28:29], v5, s[20:21] nt
	global_load_dwordx2 v[30:31], v5, s[22:23] nt
	global_load_dwordx2 v[32:33], v5, s[24:25] nt
	global_load_dwordx4 v[34:37], v6, s[26:27] nt
	global_load_dword v38, v9, s[28:29] nt
	global_load_dwordx2 v[40:41], v7, s[20:21] nt
	global_load_dwordx2 v[42:43], v7, s[22:23] nt
	global_load_dwordx2 v[44:45], v7, s[24:25] nt
	global_load_dwordx4 v[46:49], v8, s[26:27] nt
	global_load_dword v50, v10, s[28:29] nt
	s_waitcnt vmcnt(0)
